# DQK=64 fast path: row-max tree shifted one MFMA gap earlier so the rescale-threshold compare is resolved before the last PV MFMA
# baseline (speedup 1.0000x reference)
; __device__ __forceinline__ void finishSM(f32x16& p0, f32x16& p1, float alpha, float& l_reg, bf16x8& pa0, bf16x8& pa1, bf16x8& pa2, bf16x8& pa3) {
; #pragma unroll
;   for (int r = 0; r < 16; ++r) p1[r] = __builtin_amdgcn_exp2f(p1[r]);
;   float ps = 0;
; #pragma unroll
;   for (int r = 0; r < 16; ++r) ps += p0[r];
; #pragma unroll
;   for (int r = 0; r < 16; ++r) ps += p1[r];
;   { auto rr = __builtin_amdgcn_permlane32_swap(__float_as_uint(ps), __float_as_uint(ps), false, false);
;     ps = __uint_as_float(rr[0]) + __uint_as_float(rr[1]); }
;   l_reg = l_reg * alpha + ps;
;     ...
;   PK4(p0, 0, pa0); PK4(p0, 8, pa1); PK4(p1, 0, pa2); PK4(p1, 8, pa3);
;     ...
; }
; template <int DQK> __device__ __forceinline__ void qkt(f32x16& p0, f32x16& p1, const char* Ks, const bf16x8* qr, int r32, int hi, const f32x16& negm) {
; #pragma unroll
;   for (int d0 = 0; d0 < DQK / 16; ++d0) { const int cb = (d0 * 16 + hi * 8) * 2;
;     const bf16x8 b0 = *reinterpret_cast<const bf16x8*>(Ks + (DQK == 128 ? KSWZ(r32, cb) : KSWZ64(r32, cb)));
;     const bf16x8 b1 = *reinterpret_cast<const bf16x8*>(Ks + (DQK == 128 ? KSWZ(32 + r32, cb) : KSWZ64(32 + r32, cb)));
;     if (d0 == 0) { p0 = __builtin_amdgcn_mfma_f32_32x32x16_bf16(b0, qr[0], negm, 0, 0, 0); p1 = __builtin_amdgcn_mfma_f32_32x32x16_bf16(b1, qr[0], negm, 0, 0, 0); }
;     else { p0 = __builtin_amdgcn_mfma_f32_32x32x16_bf16(b0, qr[d0], p0, 0, 0, 0); p1 = __builtin_amdgcn_mfma_f32_32x32x16_bf16(b1, qr[d0], p1, 0, 0, 0); } }
; }
; __device__ __forceinline__ int v_st(int k, int c) { const int kk = (k & ~0xC) | ((k & 4) << 1) | ((k & 8) >> 1); return ((kk >> 3) * 4 + (c >> 5)) * 512 + ((kk & 7) * 32 + (c & 31)) * 2; }
; __device__ __forceinline__ int v_rd_base(int lane) { return ((lane & 3) << 3) | (((lane >> 2) & 3) << 6) | (((lane >> 4) & 1) << 5) | (((lane >> 5) & 1) << 8); }
; template <int OFF> __device__ __forceinline__ s16x4 tr_read(int vb) {
;   s16x4 r; asm volatile("ds_read_b64_tr_b16 %0, %1 offset:%2" : "=&v"(r) : "v"(vb), "i"(OFF) : "memory"); return r;
; }
; template <int D0> __device__ __forceinline__ void pv_one(f32x16& od, int vb, bf16x8 pa0, bf16x8 pa1, bf16x8 pa2, bf16x8 pa3) {
;   const s16x4 l0 = tr_read<v_rd_off(D0, 0, 0)>(vb), h0 = tr_read<v_rd_off(D0, 0, 1)>(vb), l1 = tr_read<v_rd_off(D0, 1, 0)>(vb), h1 = tr_read<v_rd_off(D0, 1, 1)>(vb);
.Lcret_f1:
	s_waitcnt lgkmcnt(4)
	v_mfma_f32_32x32x16_bf16 v[84:99], v[116:119], v[162:165], v[236:251]
	v_mfma_f32_32x32x16_bf16 v[116:131], v[180:183], v[162:165], v[236:251]
	ds_read_b128 v[180:183], v226 offset:53248
	v_add_f32_e32 v0, 0, v148
	v_add_f32_e32 v0, v178, v0
	v_add_f32_e32 v0, v146, v0
	v_add_f32_e32 v0, v149, v0
	v_add_f32_e32 v0, v144, v0
	v_add_f32_e32 v0, v147, v0
	v_add_f32_e32 v0, v143, v0
	v_add_f32_e32 v0, v145, v0
	v_add_f32_e32 v0, v137, v0
	v_add_f32_e32 v0, v139, v0
	s_waitcnt lgkmcnt(3)
	v_mfma_f32_32x32x16_bf16 v[116:131], v[184:187], v[158:161], v[116:131]
	v_add_f32_e32 v0, v136, v0
	v_add_f32_e32 v0, v138, v0
	v_add_f32_e32 v0, v135, v0
	v_add_f32_e32 v0, v142, v0
	v_add_f32_e32 v0, v140, v0
	v_add_f32_e32 v0, v141, v0
	v_mfma_f32_32x32x16_bf16 v[84:99], v[68:71], v[158:161], v[84:99]
	ds_read_b128 v[184:187], v226 offset:49152
	v_cvt_pk_bf16_f32 v76, v148, v178
	v_cvt_pk_bf16_f32 v77, v146, v149
	v_cvt_pk_bf16_f32 v78, v144, v147
	v_cvt_pk_bf16_f32 v79, v143, v145
	v_lshl_add_u64 v[148:149], v[194:195], 0, s[0:1]
	v_lshl_add_u64 v[196:197], v[192:193], 0, s[0:1]
	s_waitcnt lgkmcnt(2)
	v_mfma_f32_32x32x16_bf16 v[116:131], v[72:75], v[154:157], v[116:131]
	v_cvt_pk_bf16_f32 v80, v137, v139
	v_cvt_pk_bf16_f32 v81, v136, v138
	v_cvt_pk_bf16_f32 v82, v135, v142
	v_cvt_pk_bf16_f32 v83, v140, v141
	s_mov_b32 s4, 0x102b1000
	v_add_co_u32_e64 v132, s[4:5], s4, v148
	v_mfma_f32_32x32x16_bf16 v[84:99], v[206:209], v[154:157], v[84:99]
	ds_read_b64_tr_b16 v[134:135], v223 offset:0
	ds_read_b64_tr_b16 v[136:137], v223 offset:0x800
	ds_read_b64_tr_b16 v[138:139], v223 offset:0x200
	ds_read_b64_tr_b16 v[140:141], v223 offset:0xa00
	ds_read_b64_tr_b16 v[142:143], v223 offset:0x400
	ds_read_b64_tr_b16 v[144:145], v223 offset:0xc00
	ds_read_b64_tr_b16 v[198:199], v223 offset:0x600
	ds_read_b64_tr_b16 v[200:201], v223 offset:0xe00
	v_permlane32_swap_b32_e32 v76, v78
	v_permlane32_swap_b32_e32 v77, v79
	v_addc_co_u32_e64 v133, s[4:5], 0, v149, s[4:5]
	s_mov_b32 s4, 0x102f9000
	v_add_co_u32_e64 v202, s[4:5], s4, v148
	s_waitcnt lgkmcnt(8)
	v_mfma_f32_32x32x16_bf16 v[116:131], v[180:183], v[150:153], v[116:131]
	v_addc_co_u32_e64 v203, s[4:5], 0, v149, s[4:5]
	s_mov_b32 s4, 0x102b0000
	v_add_co_u32_e64 v204, s[4:5], s4, v196
	v_permlane32_swap_b32_e32 v80, v82
	v_permlane32_swap_b32_e32 v81, v83
	v_mfma_f32_32x32x16_bf16 v[84:99], v[184:187], v[150:153], v[84:99]
	v_addc_co_u32_e64 v205, s[4:5], 0, v197, s[4:5]
	global_load_dwordx4 v[178:181], v[132:133], off
	global_load_dwordx4 v[182:185], v[202:203], off
	global_load_dwordx4 v[186:189], v[204:205], off offset:2048
	s_waitcnt lgkmcnt(6)
	v_mfma_f32_32x32x16_bf16 v[50:65], v[76:79], v[134:137], v[50:65]
	ds_read_b64_tr_b16 v[134:135], v223 offset:0x1000
	ds_read_b64_tr_b16 v[136:137], v223 offset:0x1800
	v_exp_f32_e32 v68, v100
	v_exp_f32_e32 v69, v101
	v_add_f32_e32 v0, v68, v0
	s_waitcnt lgkmcnt(6)
	v_mfma_f32_32x32x16_bf16 v[34:49], v[76:79], v[138:141], v[34:49]
	ds_read_b64_tr_b16 v[138:139], v223 offset:0x1200
	ds_read_b64_tr_b16 v[140:141], v223 offset:0x1a00
	v_exp_f32_e32 v70, v102
	v_add_f32_e32 v0, v69, v0
	v_exp_f32_e32 v71, v103
	v_add_f32_e32 v0, v70, v0
	s_waitcnt lgkmcnt(6)
	v_mfma_f32_32x32x16_bf16 v[18:33], v[76:79], v[142:145], v[18:33]
	ds_read_b64_tr_b16 v[142:143], v223 offset:0x1400
	ds_read_b64_tr_b16 v[144:145], v223 offset:0x1c00
	v_exp_f32_e32 v72, v104
	v_add_f32_e32 v0, v71, v0
	v_exp_f32_e32 v73, v105
	v_add_f32_e32 v0, v72, v0
	s_waitcnt lgkmcnt(6)
	v_mfma_f32_32x32x16_bf16 v[2:17], v[76:79], v[198:201], v[2:17]
	ds_read_b64_tr_b16 v[198:199], v223 offset:0x1600
	ds_read_b64_tr_b16 v[200:201], v223 offset:0x1e00
	v_exp_f32_e32 v74, v106
	v_add_f32_e32 v0, v73, v0
	v_exp_f32_e32 v75, v107
	v_add_f32_e32 v0, v74, v0
	v_add_f32_e32 v0, v75, v0
	s_waitcnt lgkmcnt(6)
; #define SBAR() __builtin_amdgcn_sched_barrier(0)
; template <bool FIRST> __device__ __forceinline__ void partialSM(f32x16& p0, f32x16& p1, float& m_reg, float& alpha, f32x16& negm, float c_cur) {
;   float pmax = p0[0];
; #pragma unroll
;   for (int r = 1; r < 16; ++r) pmax = fmaxf(pmax, p0[r]);
; #pragma unroll
;   for (int r = 0; r < 16; ++r) pmax = fmaxf(pmax, p1[r]);
;   { auto rr = __builtin_amdgcn_permlane32_swap(__float_as_uint(pmax), __float_as_uint(pmax), false, false);
;     pmax = fmaxf(__uint_as_float(rr[0]), __uint_as_float(rr[1])); }
;   alpha = 1.f;
;   if (FIRST || !__builtin_expect(__all(pmax <= THR2), 1)) {
; template <int OFF> __device__ __forceinline__ s16x4 tr_read(int vb) {
;   s16x4 r; asm volatile("ds_read_b64_tr_b16 %0, %1 offset:%2" : "=&v"(r) : "v"(vb), "i"(OFF) : "memory"); return r;
; }
; template <int D0> __device__ __forceinline__ void pv_one(f32x16& od, int vb, bf16x8 pa0, bf16x8 pa1, bf16x8 pa2, bf16x8 pa3) {
;   const s16x4 l0 = tr_read<v_rd_off(D0, 0, 0)>(vb), h0 = tr_read<v_rd_off(D0, 0, 1)>(vb), l1 = tr_read<v_rd_off(D0, 1, 0)>(vb), h1 = tr_read<v_rd_off(D0, 1, 1)>(vb);
;   const s16x4 l2 = tr_read<v_rd_off(D0, 2, 0)>(vb), h2 = tr_read<v_rd_off(D0, 2, 1)>(vb), l3 = tr_read<v_rd_off(D0, 3, 0)>(vb), h3 = tr_read<v_rd_off(D0, 3, 1)>(vb);
;   asm volatile("s_waitcnt lgkmcnt(0)" ::: "memory"); SBAR();
;     ...
;   od = __builtin_amdgcn_mfma_f32_32x32x16_bf16(pa0, PK(l0, h0), od, 0, 0, 0);
;   od = __builtin_amdgcn_mfma_f32_32x32x16_bf16(pa1, PK(l1, h1), od, 0, 0, 0);
;   od = __builtin_amdgcn_mfma_f32_32x32x16_bf16(pa2, PK(l2, h2), od, 0, 0, 0);
;   od = __builtin_amdgcn_mfma_f32_32x32x16_bf16(pa3, PK(l3, h3), od, 0, 0, 0);
;     ...
; }
; __device__ __forceinline__ void pv_d0(f32x16* o, int vb, bf16x8 pa0, bf16x8 pa1, bf16x8 pa2, bf16x8 pa3) {
;   pv_one<0>(o[0], vb, pa0, pa1, pa2, pa3); pv_one<1>(o[1], vb, pa0, pa1, pa2, pa3); pv_one<2>(o[2], vb, pa0, pa1, pa2, pa3); pv_one<3>(o[3], vb, pa0, pa1, pa2, pa3);
; }
	v_mfma_f32_32x32x16_bf16 v[50:65], v[80:83], v[134:137], v[50:65]
	ds_read_b64_tr_b16 v[134:135], v223 offset:0x2000
	ds_read_b64_tr_b16 v[136:137], v223 offset:0x2800
	v_cvt_pk_bf16_f32 v100, v68, v69
	v_cvt_pk_bf16_f32 v101, v70, v71
	v_cvt_pk_bf16_f32 v102, v72, v73
	v_cvt_pk_bf16_f32 v103, v74, v75
	s_waitcnt lgkmcnt(6)
	v_mfma_f32_32x32x16_bf16 v[34:49], v[80:83], v[138:141], v[34:49]
	ds_read_b64_tr_b16 v[138:139], v223 offset:0x2200
	ds_read_b64_tr_b16 v[140:141], v223 offset:0x2a00
	v_exp_f32_e32 v68, v108
	v_exp_f32_e32 v69, v109
	v_permlane32_swap_b32_e32 v100, v102
	v_permlane32_swap_b32_e32 v101, v103
	s_waitcnt lgkmcnt(6)
	v_mfma_f32_32x32x16_bf16 v[18:33], v[80:83], v[142:145], v[18:33]
	ds_read_b64_tr_b16 v[142:143], v223 offset:0x2400
	ds_read_b64_tr_b16 v[144:145], v223 offset:0x2c00
	v_exp_f32_e32 v70, v110
	v_exp_f32_e32 v71, v111
	v_exp_f32_e32 v72, v112
	s_waitcnt lgkmcnt(6)
	v_mfma_f32_32x32x16_bf16 v[2:17], v[80:83], v[198:201], v[2:17]
	ds_read_b64_tr_b16 v[198:199], v223 offset:0x2600
	ds_read_b64_tr_b16 v[200:201], v223 offset:0x2e00
	v_exp_f32_e32 v73, v113
	v_exp_f32_e32 v74, v114
	v_exp_f32_e32 v75, v115
	s_waitcnt lgkmcnt(6)
	v_mfma_f32_32x32x16_bf16 v[50:65], v[100:103], v[134:137], v[50:65]
	ds_read_b64_tr_b16 v[134:135], v223 offset:0x3000
	ds_read_b64_tr_b16 v[136:137], v223 offset:0x3800
	v_add_f32_e32 v0, v68, v0
	v_add_f32_e32 v0, v69, v0
	v_add_f32_e32 v0, v70, v0
	v_add_f32_e32 v0, v71, v0
	s_waitcnt lgkmcnt(6)
	v_mfma_f32_32x32x16_bf16 v[34:49], v[100:103], v[138:141], v[34:49]
	ds_read_b64_tr_b16 v[138:139], v223 offset:0x3200
	ds_read_b64_tr_b16 v[140:141], v223 offset:0x3a00
	v_add_f32_e32 v0, v72, v0
	v_add_f32_e32 v0, v73, v0
	v_add_f32_e32 v0, v74, v0
	v_add_f32_e32 v0, v75, v0
	v_mov_b32_e32 v231, v0
	s_waitcnt lgkmcnt(6)
	v_mfma_f32_32x32x16_bf16 v[18:33], v[100:103], v[142:145], v[18:33]
	ds_read_b64_tr_b16 v[142:143], v223 offset:0x3400
	ds_read_b64_tr_b16 v[144:145], v223 offset:0x3c00
	v_cvt_pk_bf16_f32 v104, v68, v69
	v_cvt_pk_bf16_f32 v105, v70, v71
	v_cvt_pk_bf16_f32 v106, v72, v73
	v_cvt_pk_bf16_f32 v107, v74, v75
	v_permlane32_swap_b32_e32 v0, v231
	v_max_f32_e32 v132, v84, v85
	v_max3_f32 v132, v132, v86, v87
	s_waitcnt lgkmcnt(6)
	v_mfma_f32_32x32x16_bf16 v[2:17], v[100:103], v[198:201], v[2:17]
	ds_read_b64_tr_b16 v[198:199], v223 offset:0x3600
	ds_read_b64_tr_b16 v[200:201], v223 offset:0x3e00
	v_permlane32_swap_b32_e32 v104, v106
	v_permlane32_swap_b32_e32 v105, v107
	v_max3_f32 v132, v132, v88, v89
	v_max3_f32 v132, v132, v90, v91
	v_max3_f32 v132, v132, v92, v93
	s_waitcnt lgkmcnt(6)
	v_mfma_f32_32x32x16_bf16 v[50:65], v[104:107], v[134:137], v[50:65]
	v_max3_f32 v132, v132, v94, v95
	v_max3_f32 v132, v132, v96, v97
	v_max3_f32 v132, v132, v98, v99
	v_max3_f32 v132, v132, v116, v117
	v_max3_f32 v132, v132, v118, v119
	s_waitcnt lgkmcnt(4)
	v_mfma_f32_32x32x16_bf16 v[34:49], v[104:107], v[138:141], v[34:49]
	v_max3_f32 v132, v132, v120, v121
	v_max3_f32 v132, v132, v122, v123
	v_max3_f32 v132, v132, v124, v125
	v_max3_f32 v132, v132, v126, v127
	v_max3_f32 v132, v132, v128, v129
	v_max3_f32 v132, v132, v130, v131
	v_mov_b32_e32 v133, v132
	s_waitcnt lgkmcnt(2)
	v_mfma_f32_32x32x16_bf16 v[18:33], v[104:107], v[142:145], v[18:33]
	v_permlane32_swap_b32_e32 v132, v133
	v_max_f32_e32 v100, v132, v133
	v_cmp_ge_f32_e32 vcc, s30, v100
	s_waitcnt lgkmcnt(0)
	v_mfma_f32_32x32x16_bf16 v[2:17], v[104:107], v[198:201], v[2:17]
	s_cmp_lg_u64 vcc, exec
	s_cbranch_scc1 .LBB0_255
	s_branch .LBB0_223

; #define SBAR() __builtin_amdgcn_sched_barrier(0)
; template <bool FIRST> __device__ __forceinline__ void partialSM(f32x16& p0, f32x16& p1, float& m_reg, float& alpha, f32x16& negm, float c_cur) {
;   float pmax = p0[0];
; #pragma unroll
;   for (int r = 1; r < 16; ++r) pmax = fmaxf(pmax, p0[r]);
; #pragma unroll
;   for (int r = 0; r < 16; ++r) pmax = fmaxf(pmax, p1[r]);
;   { auto rr = __builtin_amdgcn_permlane32_swap(__float_as_uint(pmax), __float_as_uint(pmax), false, false);
;     pmax = fmaxf(__uint_as_float(rr[0]), __uint_as_float(rr[1])); }
;   alpha = 1.f;
;   if (FIRST || !__builtin_expect(__all(pmax <= THR2), 1)) {
; template <int OFF> __device__ __forceinline__ s16x4 tr_read(int vb) {
;   s16x4 r; asm volatile("ds_read_b64_tr_b16 %0, %1 offset:%2" : "=&v"(r) : "v"(vb), "i"(OFF) : "memory"); return r;
; }
; template <int D0> __device__ __forceinline__ void pv_one(f32x16& od, int vb, bf16x8 pa0, bf16x8 pa1, bf16x8 pa2, bf16x8 pa3) {
;   const s16x4 l0 = tr_read<v_rd_off(D0, 0, 0)>(vb), h0 = tr_read<v_rd_off(D0, 0, 1)>(vb), l1 = tr_read<v_rd_off(D0, 1, 0)>(vb), h1 = tr_read<v_rd_off(D0, 1, 1)>(vb);
;   const s16x4 l2 = tr_read<v_rd_off(D0, 2, 0)>(vb), h2 = tr_read<v_rd_off(D0, 2, 1)>(vb), l3 = tr_read<v_rd_off(D0, 3, 0)>(vb), h3 = tr_read<v_rd_off(D0, 3, 1)>(vb);
;   asm volatile("s_waitcnt lgkmcnt(0)" ::: "memory"); SBAR();
;     ...
;   od = __builtin_amdgcn_mfma_f32_32x32x16_bf16(pa0, PK(l0, h0), od, 0, 0, 0);
;   od = __builtin_amdgcn_mfma_f32_32x32x16_bf16(pa1, PK(l1, h1), od, 0, 0, 0);
;   od = __builtin_amdgcn_mfma_f32_32x32x16_bf16(pa2, PK(l2, h2), od, 0, 0, 0);
;   od = __builtin_amdgcn_mfma_f32_32x32x16_bf16(pa3, PK(l3, h3), od, 0, 0, 0);
;     ...
; }
; __device__ __forceinline__ void pv_d0(f32x16* o, int vb, bf16x8 pa0, bf16x8 pa1, bf16x8 pa2, bf16x8 pa3) {
;   pv_one<0>(o[0], vb, pa0, pa1, pa2, pa3); pv_one<1>(o[1], vb, pa0, pa1, pa2, pa3); pv_one<2>(o[2], vb, pa0, pa1, pa2, pa3); pv_one<3>(o[3], vb, pa0, pa1, pa2, pa3);
; }
.Lnold_h2:
	s_addk_i32 s19, 0xffa1
	s_waitcnt lgkmcnt(6)
	v_mfma_f32_32x32x16_bf16 v[50:65], v[92:95], v[134:137], v[50:65]
	ds_read_b64_tr_b16 v[134:135], v211 offset:0x1000
	ds_read_b64_tr_b16 v[136:137], v211 offset:0x1800
	v_exp_f32_e32 v84, v116
	v_exp_f32_e32 v85, v117
	v_add_f32_e32 v235, v84, v235
	s_waitcnt lgkmcnt(6)
	v_mfma_f32_32x32x16_bf16 v[34:49], v[92:95], v[138:141], v[34:49]
	ds_read_b64_tr_b16 v[138:139], v211 offset:0x1200
	ds_read_b64_tr_b16 v[140:141], v211 offset:0x1a00
	v_exp_f32_e32 v86, v118
	v_add_f32_e32 v235, v85, v235
	v_exp_f32_e32 v87, v119
	v_add_f32_e32 v235, v86, v235
	s_waitcnt lgkmcnt(6)
	v_mfma_f32_32x32x16_bf16 v[18:33], v[92:95], v[142:145], v[18:33]
	ds_read_b64_tr_b16 v[142:143], v211 offset:0x1400
	ds_read_b64_tr_b16 v[144:145], v211 offset:0x1c00
	v_exp_f32_e32 v88, v120
	v_add_f32_e32 v235, v87, v235
	v_exp_f32_e32 v89, v121
	v_add_f32_e32 v235, v88, v235
	s_waitcnt lgkmcnt(6)
	v_mfma_f32_32x32x16_bf16 v[2:17], v[92:95], v[146:149], v[2:17]
	ds_read_b64_tr_b16 v[146:147], v211 offset:0x1600
	ds_read_b64_tr_b16 v[148:149], v211 offset:0x1e00
	v_exp_f32_e32 v90, v122
	v_add_f32_e32 v235, v89, v235
	v_exp_f32_e32 v91, v123
	v_add_f32_e32 v235, v90, v235
	v_add_f32_e32 v235, v91, v235
	s_waitcnt lgkmcnt(6)
	v_mfma_f32_32x32x16_bf16 v[50:65], v[96:99], v[134:137], v[50:65]
	ds_read_b64_tr_b16 v[134:135], v211 offset:0x2000
	ds_read_b64_tr_b16 v[136:137], v211 offset:0x2800
	v_cvt_pk_bf16_f32 v116, v84, v85
	v_cvt_pk_bf16_f32 v117, v86, v87
	v_cvt_pk_bf16_f32 v118, v88, v89
	v_cvt_pk_bf16_f32 v119, v90, v91
	s_waitcnt lgkmcnt(6)
	v_mfma_f32_32x32x16_bf16 v[34:49], v[96:99], v[138:141], v[34:49]
	ds_read_b64_tr_b16 v[138:139], v211 offset:0x2200
	ds_read_b64_tr_b16 v[140:141], v211 offset:0x2a00
	v_exp_f32_e32 v84, v124
	v_exp_f32_e32 v85, v125
	v_permlane32_swap_b32_e32 v116, v118
	v_permlane32_swap_b32_e32 v117, v119
	s_waitcnt lgkmcnt(6)
	v_mfma_f32_32x32x16_bf16 v[18:33], v[96:99], v[142:145], v[18:33]
	ds_read_b64_tr_b16 v[142:143], v211 offset:0x2400
	ds_read_b64_tr_b16 v[144:145], v211 offset:0x2c00
	v_exp_f32_e32 v86, v126
	v_exp_f32_e32 v87, v127
	v_exp_f32_e32 v88, v128
	s_waitcnt lgkmcnt(6)
	v_mfma_f32_32x32x16_bf16 v[2:17], v[96:99], v[146:149], v[2:17]
	ds_read_b64_tr_b16 v[146:147], v211 offset:0x2600
	ds_read_b64_tr_b16 v[148:149], v211 offset:0x2e00
	v_exp_f32_e32 v89, v129
	v_exp_f32_e32 v90, v130
	v_exp_f32_e32 v91, v131
	s_waitcnt lgkmcnt(6)
	v_mfma_f32_32x32x16_bf16 v[50:65], v[116:119], v[134:137], v[50:65]
	ds_read_b64_tr_b16 v[134:135], v211 offset:0x3000
	ds_read_b64_tr_b16 v[136:137], v211 offset:0x3800
	v_add_f32_e32 v235, v84, v235
	v_add_f32_e32 v235, v85, v235
	v_add_f32_e32 v235, v86, v235
	v_add_f32_e32 v235, v87, v235
	s_waitcnt lgkmcnt(6)
	v_mfma_f32_32x32x16_bf16 v[34:49], v[116:119], v[138:141], v[34:49]
	ds_read_b64_tr_b16 v[138:139], v211 offset:0x3200
	ds_read_b64_tr_b16 v[140:141], v211 offset:0x3a00
	v_add_f32_e32 v235, v88, v235
	v_add_f32_e32 v235, v89, v235
	v_add_f32_e32 v235, v90, v235
	v_add_f32_e32 v235, v91, v235
	v_mov_b32_e32 v252, v235
	s_waitcnt lgkmcnt(6)
	v_mfma_f32_32x32x16_bf16 v[18:33], v[116:119], v[142:145], v[18:33]
	ds_read_b64_tr_b16 v[142:143], v211 offset:0x3400
	ds_read_b64_tr_b16 v[144:145], v211 offset:0x3c00
	v_cvt_pk_bf16_f32 v120, v84, v85
	v_cvt_pk_bf16_f32 v121, v86, v87
	v_cvt_pk_bf16_f32 v122, v88, v89
	v_cvt_pk_bf16_f32 v123, v90, v91
	v_permlane32_swap_b32_e32 v235, v252
	v_max_f32_e32 v132, v68, v69
	v_max3_f32 v132, v132, v70, v71
	s_waitcnt lgkmcnt(6)
	v_mfma_f32_32x32x16_bf16 v[2:17], v[116:119], v[146:149], v[2:17]
	ds_read_b64_tr_b16 v[146:147], v211 offset:0x3600
	ds_read_b64_tr_b16 v[148:149], v211 offset:0x3e00
	v_permlane32_swap_b32_e32 v120, v122
	v_permlane32_swap_b32_e32 v121, v123
	v_max3_f32 v132, v132, v72, v73
	v_max3_f32 v132, v132, v74, v75
	v_max3_f32 v132, v132, v76, v77
	s_waitcnt lgkmcnt(6)
	v_mfma_f32_32x32x16_bf16 v[50:65], v[120:123], v[134:137], v[50:65]
	v_max3_f32 v132, v132, v78, v79
	v_max3_f32 v132, v132, v80, v81
	v_max3_f32 v132, v132, v82, v83
	v_max3_f32 v132, v132, v100, v101
	v_max3_f32 v132, v132, v102, v103
	s_waitcnt lgkmcnt(4)
	v_mfma_f32_32x32x16_bf16 v[34:49], v[120:123], v[138:141], v[34:49]
	v_max3_f32 v132, v132, v104, v105
	v_max3_f32 v132, v132, v106, v107
	v_max3_f32 v132, v132, v108, v109
	v_max3_f32 v132, v132, v110, v111
	v_max3_f32 v132, v132, v112, v113
	v_max3_f32 v132, v132, v114, v115
	v_mov_b32_e32 v133, v132
	s_waitcnt lgkmcnt(2)
	v_mfma_f32_32x32x16_bf16 v[18:33], v[120:123], v[142:145], v[18:33]
	v_permlane32_swap_b32_e32 v132, v133
	v_max_f32_e32 v196, v132, v133
	v_cmp_ge_f32_e32 vcc, s30, v196
	s_waitcnt lgkmcnt(0)
	v_mfma_f32_32x32x16_bf16 v[2:17], v[120:123], v[146:149], v[2:17]
	s_cmp_lg_u64 vcc, exec
	s_cbranch_scc1 .LBB0_259
	s_branch .LBB0_241
